# scan-state loops: top vmcnt ladder peeled to entry path; natten QK^T K-fragment LDS reads software-pipelined (3 pairs in flight)
# speedup vs baseline: 1.0020x; 1.0020x over previous
; #define GAS __attribute__((address_space(1)))
; __device__ __forceinline__ unsigned pk2(float lo, float hi) { const f32x2_t v = {lo, hi}; const bf16x2_t b = __builtin_convertvector(v, bf16x2_t); return __builtin_bit_cast(unsigned, b); }
; template <int DK> __device__ __forceinline__ void scan_state_unit(const ScanBufs<DK>& S, int unit, int lane, bool skip_ctx_store) {
;     ...
;     for (int s = 0; s < 36; ++s) {
;         const int g = scan_chunk(b, dir, s);
;         if (s + 1 < 36) p2_load<DK>(nxt, S, dir, scan_chunk(b, dir, s + 1), h, dkb, dvb, r, hi);
;         if (!(skip_ctx_store && s < 4)) {
;             bf16* sp = S.SP + (((((size_t)dir * NCH + g) * 8 + h) * (DK / 8) + dkb * 4) * 128 + dvb * 64 + r) * 8 + 4 * hi;
; #pragma unroll
;             for (int j = 0; j < 2; ++j)
; #pragma unroll
;                 for (int q = 0; q < 4; ++q) { v2u o; o.x = pk2(acc[j][4 * q], acc[j][4 * q + 1]); o.y = pk2(acc[j][4 * q + 2], acc[j][4 * q + 3]); *(GAS v2u*)(sp + ((size_t)q * 128 + j * 32) * 8) = o; }
;         }
; #pragma unroll
;         for (int j = 0; j < 2; ++j)
; #pragma unroll
;             for (int q = 0; q < 4; ++q)
; #pragma unroll
;                 for (int i = 0; i < 4; ++i) acc[j][4 * q + i] *= cur.ae[q][i];
; #pragma unroll
;         for (int kk = 0; kk < 4; ++kk) { acc[0] = __builtin_amdgcn_mfma_f32_32x32x16_bf16(cur.a[kk], cur.bv[0][kk], acc[0], 0, 0, 0); acc[1] = __builtin_amdgcn_mfma_f32_32x32x16_bf16(cur.a[kk], cur.bv[1][kk], acc[1], 0, 0, 0); }
.LBB0_915:
	s_waitcnt vmcnt(28)
	v_pk_mul_f32 v[2:3], v[92:93], v[2:3]
	v_pk_mul_f32 v[0:1], v[90:91], v[0:1]
	s_waitcnt vmcnt(24)
	v_pk_mul_f32 v[6:7], v[124:125], v[6:7]
	v_pk_mul_f32 v[4:5], v[122:123], v[4:5]
	s_waitcnt vmcnt(20)
	v_pk_mul_f32 v[10:11], v[144:145], v[10:11]
	v_pk_mul_f32 v[8:9], v[142:143], v[8:9]
	s_waitcnt vmcnt(16)
	v_pk_mul_f32 v[14:15], v[156:157], v[14:15]
	v_pk_mul_f32 v[12:13], v[154:155], v[12:13]
	v_pk_mul_f32 v[30:31], v[156:157], v[30:31]
	v_pk_mul_f32 v[26:27], v[144:145], v[26:27]
	v_pk_mul_f32 v[22:23], v[124:125], v[22:23]
	v_pk_mul_f32 v[18:19], v[92:93], v[18:19]
	v_pk_mul_f32 v[16:17], v[90:91], v[16:17]
	v_pk_mul_f32 v[28:29], v[154:155], v[28:29]
	v_pk_mul_f32 v[24:25], v[142:143], v[24:25]
	v_pk_mul_f32 v[20:21], v[122:123], v[20:21]
	v_mfma_f32_32x32x16_bf16 v[0:15], v[52:55], v[102:105], v[0:15]
	s_andn2_b64 vcc, exec, s[0:1]
	v_readlane_b32 s0, v250, 41
	v_readlane_b32 s1, v250, 42
	s_movk_i32 s9, 0x2000
	s_movk_i32 s10, 0x3000
	v_mfma_f32_32x32x16_bf16 v[16:31], v[52:55], v[56:59], v[16:31]
	v_lshl_add_u64 v[52:53], s[0:1], 0, v[180:181]
	v_readlane_b32 s0, v246, 18
	s_mov_b32 s1, 1
	s_nop 0
	v_or_b32_e32 v54, s0, v178
	s_mov_b32 s0, 31
	v_mfma_f32_32x32x16_bf16 v[0:15], v[60:63], v[74:77], v[0:15]
	v_mfma_f32_32x32x16_bf16 v[16:31], v[60:63], v[70:73], v[16:31]
	v_mfma_f32_32x32x16_bf16 v[0:15], v[82:85], v[118:121], v[0:15]
	v_mfma_f32_32x32x16_bf16 v[16:31], v[82:85], v[114:117], v[16:31]
	v_mfma_f32_32x32x16_bf16 v[0:15], v[66:69], v[130:133], v[0:15]
	v_mfma_f32_32x32x16_bf16 v[16:31], v[66:69], v[78:81], v[16:31]
	s_add_i32 s6, s1, -1
	s_and_b64 s[2:3], s[78:79], exec
	s_cselect_b32 s2, s6, s0
	s_add_i32 s0, s0, -1
	s_add_i32 s8, s2, s59
	s_and_b64 s[2:3], s[78:79], exec
	s_cselect_b32 s2, s1, s0
	s_add_i32 s2, s2, s59
	s_ashr_i32 s3, s2, 31
	s_add_u32 s6, s2, s25
	s_nop 0
	v_cvt_pk_bf16_f32 v82, v0, v1
	v_cvt_pk_bf16_f32 v83, v2, v3
	v_cvt_pk_bf16_f32 v84, v4, v5
	v_cvt_pk_bf16_f32 v85, v6, v7
	v_cvt_pk_bf16_f32 v90, v8, v9
	v_cvt_pk_bf16_f32 v91, v10, v11
	v_cvt_pk_bf16_f32 v92, v12, v13
	v_cvt_pk_bf16_f32 v93, v14, v15
	v_cvt_pk_bf16_f32 v102, v16, v17
	v_cvt_pk_bf16_f32 v103, v18, v19
	v_cvt_pk_bf16_f32 v104, v20, v21
	v_cvt_pk_bf16_f32 v105, v22, v23
	v_cvt_pk_bf16_f32 v114, v24, v25
	v_cvt_pk_bf16_f32 v115, v26, v27
	v_cvt_pk_bf16_f32 v116, v28, v29
	v_cvt_pk_bf16_f32 v117, v30, v31
	s_waitcnt vmcnt(12)
	v_pk_mul_f32 v[0:1], v[138:139], v[0:1]
	v_pk_mul_f32 v[2:3], v[140:141], v[2:3]
	s_waitcnt vmcnt(8)
	v_pk_mul_f32 v[4:5], v[146:147], v[4:5]
	v_pk_mul_f32 v[6:7], v[148:149], v[6:7]
	s_waitcnt vmcnt(4)
	v_pk_mul_f32 v[8:9], v[150:151], v[8:9]
	v_pk_mul_f32 v[10:11], v[152:153], v[10:11]
	s_waitcnt vmcnt(0)
	s_branch .Lsc916_mid
.LBB0_916:
	s_add_i32 s6, s1, -1
	s_and_b64 s[2:3], s[78:79], exec
	s_cselect_b32 s2, s6, s0
	s_add_i32 s0, s0, -1
	s_add_i32 s8, s2, s59
	s_and_b64 s[2:3], s[78:79], exec
	s_cselect_b32 s2, s1, s0
	s_add_i32 s2, s2, s59
	s_ashr_i32 s3, s2, 31
	s_add_u32 s6, s2, s25
	s_nop 0
	v_cvt_pk_bf16_f32 v82, v0, v1
	v_cvt_pk_bf16_f32 v83, v2, v3
	v_cvt_pk_bf16_f32 v84, v4, v5
	v_cvt_pk_bf16_f32 v85, v6, v7
	v_cvt_pk_bf16_f32 v90, v8, v9
	v_cvt_pk_bf16_f32 v91, v10, v11
	v_cvt_pk_bf16_f32 v92, v12, v13
	v_cvt_pk_bf16_f32 v93, v14, v15
	v_cvt_pk_bf16_f32 v102, v16, v17
	v_cvt_pk_bf16_f32 v103, v18, v19
	v_cvt_pk_bf16_f32 v104, v20, v21
	v_cvt_pk_bf16_f32 v105, v22, v23
	v_cvt_pk_bf16_f32 v114, v24, v25
	v_cvt_pk_bf16_f32 v115, v26, v27
	v_cvt_pk_bf16_f32 v116, v28, v29
	v_cvt_pk_bf16_f32 v117, v30, v31
	v_pk_mul_f32 v[0:1], v[138:139], v[0:1]
	v_pk_mul_f32 v[2:3], v[140:141], v[2:3]
	v_pk_mul_f32 v[4:5], v[146:147], v[4:5]
	v_pk_mul_f32 v[6:7], v[148:149], v[6:7]
	v_pk_mul_f32 v[8:9], v[150:151], v[8:9]
	v_pk_mul_f32 v[10:11], v[152:153], v[10:11]
; #define GAS __attribute__((address_space(1)))
; __device__ __forceinline__ unsigned pk2(float lo, float hi) { const f32x2_t v = {lo, hi}; const bf16x2_t b = __builtin_convertvector(v, bf16x2_t); return __builtin_bit_cast(unsigned, b); }
; template <int DK> __device__ __forceinline__ void scan_state_unit(const ScanBufs<DK>& S, int unit, int lane, bool skip_ctx_store) {
;     ...
;     for (int s = 0; s < 36; ++s) {
;         const int g = scan_chunk(b, dir, s);
;         if (s + 1 < 36) p2_load<DK>(nxt, S, dir, scan_chunk(b, dir, s + 1), h, dkb, dvb, r, hi);
;         if (!(skip_ctx_store && s < 4)) {
;             bf16* sp = S.SP + (((((size_t)dir * NCH + g) * 8 + h) * (DK / 8) + dkb * 4) * 128 + dvb * 64 + r) * 8 + 4 * hi;
; #pragma unroll
;             for (int j = 0; j < 2; ++j)
; #pragma unroll
;                 for (int q = 0; q < 4; ++q) { v2u o; o.x = pk2(acc[j][4 * q], acc[j][4 * q + 1]); o.y = pk2(acc[j][4 * q + 2], acc[j][4 * q + 3]); *(GAS v2u*)(sp + ((size_t)q * 128 + j * 32) * 8) = o; }
;         }
; #pragma unroll
;         for (int j = 0; j < 2; ++j)
; #pragma unroll
;             for (int q = 0; q < 4; ++q)
; #pragma unroll
;                 for (int i = 0; i < 4; ++i) acc[j][4 * q + i] *= cur.ae[q][i];
; #pragma unroll
;         for (int kk = 0; kk < 4; ++kk) { acc[0] = __builtin_amdgcn_mfma_f32_32x32x16_bf16(cur.a[kk], cur.bv[0][kk], acc[0], 0, 0, 0); acc[1] = __builtin_amdgcn_mfma_f32_32x32x16_bf16(cur.a[kk], cur.bv[1][kk], acc[1], 0, 0, 0); }
;         cur = nxt;
;     }
.Lsc916_mid:
	v_pk_mul_f32 v[12:13], v[158:159], v[12:13]
	v_pk_mul_f32 v[14:15], v[160:161], v[14:15]
	v_pk_mul_f32 v[30:31], v[160:161], v[30:31]
	v_pk_mul_f32 v[26:27], v[152:153], v[26:27]
	v_pk_mul_f32 v[22:23], v[148:149], v[22:23]
	v_pk_mul_f32 v[18:19], v[140:141], v[18:19]
	v_pk_mul_f32 v[16:17], v[138:139], v[16:17]
	v_pk_mul_f32 v[28:29], v[158:159], v[28:29]
	v_pk_mul_f32 v[24:25], v[150:151], v[24:25]
	v_pk_mul_f32 v[20:21], v[146:147], v[20:21]
	s_addc_u32 s7, s3, 0
	s_lshl_b64 s[2:3], s[2:3], 17
	v_mfma_f32_32x32x16_bf16 v[0:15], v[110:113], v[134:137], v[0:15]
	v_lshl_add_u64 v[56:57], v[52:53], 0, s[2:3]
	v_add_co_u32_e32 v60, vcc, s10, v56
	s_lshl_b64 s[6:7], s[6:7], 3
	s_nop 0
	v_addc_co_u32_e32 v61, vcc, 0, v57, vcc
	v_add_co_u32_e32 v70, vcc, s9, v56
	v_mfma_f32_32x32x16_bf16 v[16:31], v[110:113], v[94:97], v[16:31]
	s_or_b64 s[2:3], s[6:7], s[60:61]
	v_addc_co_u32_e32 v71, vcc, 0, v57, vcc
	v_add_co_u32_e32 v74, vcc, s67, v56
	s_lshl_b64 s[6:7], s[2:3], 8
	s_lshl_b64 s[2:3], s[2:3], 13
	v_addc_co_u32_e32 v75, vcc, 0, v57, vcc
	v_lshl_add_u64 v[76:77], v[184:185], 0, s[2:3]
	v_add_co_u32_e32 v78, vcc, s67, v76
	v_mfma_f32_32x32x16_bf16 v[0:15], v[98:101], v[126:129], v[0:15]
	global_load_dwordx4 v[94:97], v[56:57], off offset:512
	global_load_dwordx4 v[134:137], v[56:57], off
	s_nop 0
	global_load_dwordx4 v[56:59], v[60:61], off offset:512
	s_nop 0
	global_load_dwordx4 v[60:63], v[60:61], off
	v_addc_co_u32_e32 v79, vcc, 0, v77, vcc
	s_ashr_i32 s3, s8, 31
	s_add_u32 s2, s8, s25
	s_addc_u32 s3, s3, 0
	v_mfma_f32_32x32x16_bf16 v[16:31], v[98:101], v[106:109], v[16:31]
	global_load_dwordx4 v[66:69], v[70:71], off offset:512
	s_nop 0
	global_load_dwordx4 v[70:73], v[70:71], off
	s_nop 0
	global_load_dwordx4 v[106:109], v[74:75], off offset:512
	global_load_dwordx4 v[126:129], v[74:75], off
	v_lshl_add_u64 v[74:75], v[186:187], 0, s[6:7]
	global_load_dwordx4 v[158:161], v[74:75], off offset:96
	global_load_dwordx4 v[150:153], v[74:75], off offset:64
	global_load_dwordx4 v[146:149], v[74:75], off offset:32
	global_load_dwordx4 v[138:141], v[74:75], off
	global_load_dwordx4 v[98:101], v[76:77], off offset:2048
	global_load_dwordx4 v[110:113], v[76:77], off
	s_nop 0
	global_load_dwordx4 v[74:77], v[78:79], off offset:2048
	s_lshl_b64 s[2:3], s[2:3], 17
	global_load_dwordx4 v[78:81], v[78:79], off
	s_add_i32 s1, s1, 1
	s_cmp_eq_u32 s0, 0
	v_mfma_f32_32x32x16_bf16 v[0:15], v[32:35], v[86:89], v[0:15]
	v_lshl_or_b32 v86, v54, 4, s2
	v_mov_b32_e32 v87, s3
	v_mfma_f32_32x32x16_bf16 v[16:31], v[32:35], v[40:43], v[16:31]
	v_lshl_add_u64 v[32:33], v[182:183], 0, v[86:87]
	v_add_co_u32_e32 v34, vcc, s67, v32
	global_store_dwordx2 v[32:33], v[82:83], off
	global_store_dwordx2 v[32:33], v[84:85], off offset:2048
	v_addc_co_u32_e32 v35, vcc, 0, v33, vcc
	global_store_dwordx2 v[32:33], v[102:103], off offset:512
	global_store_dwordx2 v[32:33], v[104:105], off offset:2560
	global_store_dwordx2 v[34:35], v[90:91], off
	global_store_dwordx2 v[34:35], v[92:93], off offset:2048
	global_store_dwordx2 v[34:35], v[114:115], off offset:512
	global_store_dwordx2 v[34:35], v[116:117], off offset:2560
	v_mfma_f32_32x32x16_bf16 v[0:15], v[44:47], v[48:51], v[0:15]
	s_waitcnt vmcnt(20)
	v_mov_b64_e32 v[48:49], v[60:61]
	v_mfma_f32_32x32x16_bf16 v[16:31], v[44:47], v[36:39], v[16:31]
	v_mov_b64_e32 v[36:37], v[56:57]
	v_mov_b64_e32 v[38:39], v[58:59]
	s_waitcnt vmcnt(19)
	v_mov_b64_e32 v[40:41], v[66:67]
	s_waitcnt vmcnt(18)
	v_mov_b64_e32 v[88:89], v[72:73]
	v_mov_b64_e32 v[42:43], v[68:69]
	v_mov_b64_e32 v[50:51], v[62:63]
	v_mov_b64_e32 v[86:87], v[70:71]
	s_waitcnt vmcnt(9)
	v_mov_b64_e32 v[44:45], v[74:75]
	v_mov_b64_e32 v[46:47], v[76:77]
	s_waitcnt vmcnt(8)
	v_mov_b64_e32 v[32:33], v[78:79]
	v_mov_b64_e32 v[34:35], v[80:81]
	s_cbranch_scc0 .LBB0_916
	v_readlane_b32 s0, v246, 19
	v_readlane_b32 s1, v246, 20
	v_cvt_pk_bf16_f32 v0, v0, v1
	v_or_b32_e32 v32, s0, v178
	v_mov_b32_e32 v33, s1
	v_lshl_add_u64 v[32:33], v[32:33], 4, v[182:183]
	v_cvt_pk_bf16_f32 v1, v2, v3
	global_store_dwordx2 v[32:33], v[0:1], off
	s_mov_b64 s[0:1], -1
	s_branch .LBB0_919

; #define GAS __attribute__((address_space(1)))
; __device__ __forceinline__ unsigned pk2(float lo, float hi) { const f32x2_t v = {lo, hi}; const bf16x2_t b = __builtin_convertvector(v, bf16x2_t); return __builtin_bit_cast(unsigned, b); }
; template <int DK> __device__ __forceinline__ void scan_state_unit(const ScanBufs<DK>& S, int unit, int lane, bool skip_ctx_store) {
;     ...
;     for (int s = 0; s < 36; ++s) {
;         const int g = scan_chunk(b, dir, s);
;         if (s + 1 < 36) p2_load<DK>(nxt, S, dir, scan_chunk(b, dir, s + 1), h, dkb, dvb, r, hi);
;         if (!(skip_ctx_store && s < 4)) {
;             bf16* sp = S.SP + (((((size_t)dir * NCH + g) * 8 + h) * (DK / 8) + dkb * 4) * 128 + dvb * 64 + r) * 8 + 4 * hi;
; #pragma unroll
;             for (int j = 0; j < 2; ++j)
; #pragma unroll
;                 for (int q = 0; q < 4; ++q) { v2u o; o.x = pk2(acc[j][4 * q], acc[j][4 * q + 1]); o.y = pk2(acc[j][4 * q + 2], acc[j][4 * q + 3]); *(GAS v2u*)(sp + ((size_t)q * 128 + j * 32) * 8) = o; }
;         }
; #pragma unroll
;         for (int j = 0; j < 2; ++j)
; #pragma unroll
;             for (int q = 0; q < 4; ++q)
; #pragma unroll
;                 for (int i = 0; i < 4; ++i) acc[j][4 * q + i] *= cur.ae[q][i];
; #pragma unroll
;         for (int kk = 0; kk < 4; ++kk) { acc[0] = __builtin_amdgcn_mfma_f32_32x32x16_bf16(cur.a[kk], cur.bv[0][kk], acc[0], 0, 0, 0); acc[1] = __builtin_amdgcn_mfma_f32_32x32x16_bf16(cur.a[kk], cur.bv[1][kk], acc[1], 0, 0, 0); }
.LBB0_930:
	s_waitcnt vmcnt(28)
	v_pk_mul_f32 v[2:3], v[80:81], v[2:3]
	v_pk_mul_f32 v[0:1], v[78:79], v[0:1]
	s_waitcnt vmcnt(24)
	v_pk_mul_f32 v[6:7], v[116:117], v[6:7]
	v_pk_mul_f32 v[4:5], v[114:115], v[4:5]
	s_waitcnt vmcnt(20)
	v_pk_mul_f32 v[10:11], v[132:133], v[10:11]
	v_pk_mul_f32 v[8:9], v[130:131], v[8:9]
	s_waitcnt vmcnt(16)
	v_pk_mul_f32 v[14:15], v[152:153], v[14:15]
	v_pk_mul_f32 v[12:13], v[150:151], v[12:13]
	v_pk_mul_f32 v[30:31], v[152:153], v[30:31]
	v_pk_mul_f32 v[26:27], v[132:133], v[26:27]
	v_pk_mul_f32 v[22:23], v[116:117], v[22:23]
	v_pk_mul_f32 v[18:19], v[80:81], v[18:19]
	v_pk_mul_f32 v[16:17], v[78:79], v[16:17]
	v_pk_mul_f32 v[28:29], v[150:151], v[28:29]
	v_pk_mul_f32 v[24:25], v[130:131], v[24:25]
	v_pk_mul_f32 v[20:21], v[114:115], v[20:21]
	v_mfma_f32_32x32x16_bf16 v[0:15], v[52:55], v[106:109], v[0:15]
	v_readlane_b32 s0, v251, 23
	v_readlane_b32 s1, v251, 24
	s_movk_i32 s7, 0x2000
	s_movk_i32 s8, 0x3000
	v_mfma_f32_32x32x16_bf16 v[16:31], v[52:55], v[56:59], v[16:31]
	v_lshl_add_u64 v[54:55], s[0:1], 0, v[184:185]
	v_lshl_add_u64 v[52:53], v[178:179], 0, v[186:187]
	s_mov_b32 s0, 31
	s_mov_b32 s1, 1
	v_mfma_f32_32x32x16_bf16 v[0:15], v[60:63], v[86:89], v[0:15]
	v_mfma_f32_32x32x16_bf16 v[16:31], v[60:63], v[82:85], v[16:31]
	v_mfma_f32_32x32x16_bf16 v[0:15], v[90:93], v[98:101], v[0:15]
	v_mfma_f32_32x32x16_bf16 v[16:31], v[90:93], v[94:97], v[16:31]
	v_mfma_f32_32x32x16_bf16 v[0:15], v[66:69], v[122:125], v[0:15]
	v_mfma_f32_32x32x16_bf16 v[16:31], v[66:69], v[74:77], v[16:31]
	s_add_i32 s4, s1, -1
	s_and_b64 s[2:3], s[26:27], exec
	s_cselect_b32 s2, s4, s0
	s_add_i32 s0, s0, -1
	s_add_i32 s6, s2, s63
	s_and_b64 s[2:3], s[26:27], exec
	s_cselect_b32 s2, s1, s0
	s_add_i32 s2, s2, s63
	s_ashr_i32 s3, s2, 31
	s_add_u32 s4, s2, s62
	s_addc_u32 s5, s3, 0
	s_lshl_b64 s[2:3], s[2:3], 17
	v_lshl_add_u64 v[66:67], v[54:55], 0, s[2:3]
	v_add_co_u32_e32 v74, vcc, s8, v66
	v_cvt_pk_bf16_f32 v56, v0, v1
	s_nop 0
	v_addc_co_u32_e32 v75, vcc, 0, v67, vcc
	v_cvt_pk_bf16_f32 v57, v2, v3
	v_cvt_pk_bf16_f32 v60, v4, v5
	v_cvt_pk_bf16_f32 v61, v6, v7
	v_cvt_pk_bf16_f32 v58, v8, v9
	v_cvt_pk_bf16_f32 v59, v10, v11
	v_cvt_pk_bf16_f32 v62, v12, v13
	v_cvt_pk_bf16_f32 v63, v14, v15
	v_cvt_pk_bf16_f32 v94, v16, v17
	v_cvt_pk_bf16_f32 v95, v18, v19
	v_cvt_pk_bf16_f32 v96, v20, v21
	v_cvt_pk_bf16_f32 v97, v22, v23
	v_cvt_pk_bf16_f32 v98, v24, v25
	v_cvt_pk_bf16_f32 v99, v26, v27
	v_cvt_pk_bf16_f32 v100, v28, v29
	v_cvt_pk_bf16_f32 v101, v30, v31
	s_waitcnt vmcnt(12)
	v_pk_mul_f32 v[0:1], v[138:139], v[0:1]
	v_pk_mul_f32 v[2:3], v[140:141], v[2:3]
	s_waitcnt vmcnt(8)
	v_pk_mul_f32 v[4:5], v[146:147], v[4:5]
	v_pk_mul_f32 v[6:7], v[148:149], v[6:7]
	s_waitcnt vmcnt(4)
	v_pk_mul_f32 v[8:9], v[154:155], v[8:9]
	v_pk_mul_f32 v[10:11], v[156:157], v[10:11]
	s_waitcnt vmcnt(0)
	s_branch .Lsc931_mid
.LBB0_931:
	s_add_i32 s4, s1, -1
	s_and_b64 s[2:3], s[26:27], exec
	s_cselect_b32 s2, s4, s0
	s_add_i32 s0, s0, -1
	s_add_i32 s6, s2, s63
	s_and_b64 s[2:3], s[26:27], exec
	s_cselect_b32 s2, s1, s0
	s_add_i32 s2, s2, s63
	s_ashr_i32 s3, s2, 31
	s_add_u32 s4, s2, s62
	s_addc_u32 s5, s3, 0
	s_lshl_b64 s[2:3], s[2:3], 17
	v_lshl_add_u64 v[66:67], v[54:55], 0, s[2:3]
	v_add_co_u32_e32 v74, vcc, s8, v66
	v_cvt_pk_bf16_f32 v56, v0, v1
	s_nop 0
	v_addc_co_u32_e32 v75, vcc, 0, v67, vcc
	v_cvt_pk_bf16_f32 v57, v2, v3
	v_cvt_pk_bf16_f32 v60, v4, v5
	v_cvt_pk_bf16_f32 v61, v6, v7
	v_cvt_pk_bf16_f32 v58, v8, v9
	v_cvt_pk_bf16_f32 v59, v10, v11
	v_cvt_pk_bf16_f32 v62, v12, v13
	v_cvt_pk_bf16_f32 v63, v14, v15
	v_cvt_pk_bf16_f32 v94, v16, v17
	v_cvt_pk_bf16_f32 v95, v18, v19
	v_cvt_pk_bf16_f32 v96, v20, v21
	v_cvt_pk_bf16_f32 v97, v22, v23
	v_cvt_pk_bf16_f32 v98, v24, v25
	v_cvt_pk_bf16_f32 v99, v26, v27
	v_cvt_pk_bf16_f32 v100, v28, v29
	v_cvt_pk_bf16_f32 v101, v30, v31
	v_pk_mul_f32 v[0:1], v[138:139], v[0:1]
	v_pk_mul_f32 v[2:3], v[140:141], v[2:3]
	v_pk_mul_f32 v[4:5], v[146:147], v[4:5]
	v_pk_mul_f32 v[6:7], v[148:149], v[6:7]
	v_pk_mul_f32 v[8:9], v[154:155], v[8:9]
	v_pk_mul_f32 v[10:11], v[156:157], v[10:11]
; #define GAS __attribute__((address_space(1)))
; __device__ __forceinline__ unsigned pk2(float lo, float hi) { const f32x2_t v = {lo, hi}; const bf16x2_t b = __builtin_convertvector(v, bf16x2_t); return __builtin_bit_cast(unsigned, b); }
; template <int DK> __device__ __forceinline__ void scan_state_unit(const ScanBufs<DK>& S, int unit, int lane, bool skip_ctx_store) {
;     ...
;     for (int s = 0; s < 36; ++s) {
;         const int g = scan_chunk(b, dir, s);
;         if (s + 1 < 36) p2_load<DK>(nxt, S, dir, scan_chunk(b, dir, s + 1), h, dkb, dvb, r, hi);
;         if (!(skip_ctx_store && s < 4)) {
;             bf16* sp = S.SP + (((((size_t)dir * NCH + g) * 8 + h) * (DK / 8) + dkb * 4) * 128 + dvb * 64 + r) * 8 + 4 * hi;
; #pragma unroll
;             for (int j = 0; j < 2; ++j)
; #pragma unroll
;                 for (int q = 0; q < 4; ++q) { v2u o; o.x = pk2(acc[j][4 * q], acc[j][4 * q + 1]); o.y = pk2(acc[j][4 * q + 2], acc[j][4 * q + 3]); *(GAS v2u*)(sp + ((size_t)q * 128 + j * 32) * 8) = o; }
;         }
; #pragma unroll
;         for (int j = 0; j < 2; ++j)
; #pragma unroll
;             for (int q = 0; q < 4; ++q)
; #pragma unroll
;                 for (int i = 0; i < 4; ++i) acc[j][4 * q + i] *= cur.ae[q][i];
; #pragma unroll
;         for (int kk = 0; kk < 4; ++kk) { acc[0] = __builtin_amdgcn_mfma_f32_32x32x16_bf16(cur.a[kk], cur.bv[0][kk], acc[0], 0, 0, 0); acc[1] = __builtin_amdgcn_mfma_f32_32x32x16_bf16(cur.a[kk], cur.bv[1][kk], acc[1], 0, 0, 0); }
;         cur = nxt;
;     }
.Lsc931_mid:
	v_pk_mul_f32 v[12:13], v[158:159], v[12:13]
	v_pk_mul_f32 v[14:15], v[160:161], v[14:15]
	v_pk_mul_f32 v[30:31], v[160:161], v[30:31]
	v_pk_mul_f32 v[26:27], v[156:157], v[26:27]
	v_pk_mul_f32 v[22:23], v[148:149], v[22:23]
	v_pk_mul_f32 v[18:19], v[140:141], v[18:19]
	v_pk_mul_f32 v[16:17], v[138:139], v[16:17]
	v_pk_mul_f32 v[28:29], v[158:159], v[28:29]
	v_pk_mul_f32 v[24:25], v[154:155], v[24:25]
	v_pk_mul_f32 v[20:21], v[146:147], v[20:21]
	s_lshl_b64 s[4:5], s[4:5], 3
	v_add_co_u32_e32 v82, vcc, s7, v66
	v_mfma_f32_32x32x16_bf16 v[0:15], v[126:129], v[134:137], v[0:15]
	s_or_b64 s[2:3], s[4:5], s[64:65]
	v_addc_co_u32_e32 v83, vcc, 0, v67, vcc
	v_add_co_u32_e32 v90, vcc, s67, v66
	s_lshl_b64 s[4:5], s[2:3], 9
	s_lshl_b64 s[2:3], s[2:3], 14
	v_mfma_f32_32x32x16_bf16 v[16:31], v[126:129], v[102:105], v[16:31]
	v_addc_co_u32_e32 v91, vcc, 0, v67, vcc
	v_lshl_add_u64 v[106:107], v[182:183], 0, s[2:3]
	v_add_co_u32_e32 v92, vcc, s8, v106
	global_load_dwordx4 v[102:105], v[66:67], off offset:512
	global_load_dwordx4 v[134:137], v[66:67], off
	v_addc_co_u32_e32 v93, vcc, 0, v107, vcc
	v_add_co_u32_e32 v88, vcc, s7, v106
	global_load_dwordx4 v[66:69], v[74:75], off offset:512
	s_nop 0
	global_load_dwordx4 v[74:77], v[74:75], off
	v_addc_co_u32_e32 v89, vcc, 0, v107, vcc
	v_lshl_add_u64 v[86:87], v[180:181], 0, s[4:5]
	v_add_co_u32_e32 v108, vcc, s67, v106
	v_mfma_f32_32x32x16_bf16 v[0:15], v[110:113], v[142:145], v[0:15]
	s_nop 0
	v_addc_co_u32_e32 v109, vcc, 0, v107, vcc
	s_ashr_i32 s3, s6, 31
	s_add_u32 s2, s6, s62
	s_addc_u32 s3, s3, 0
	s_lshl_b64 s[2:3], s[2:3], 18
	s_add_i32 s1, s1, 1
	v_mfma_f32_32x32x16_bf16 v[16:31], v[110:113], v[118:121], v[16:31]
	global_load_dwordx4 v[78:81], v[82:83], off offset:512
	s_nop 0
	global_load_dwordx4 v[82:85], v[82:83], off
	s_nop 0
	global_load_dwordx4 v[118:121], v[90:91], off offset:512
	global_load_dwordx4 v[158:161], v[86:87], off offset:96
	global_load_dwordx4 v[154:157], v[86:87], off offset:64
	global_load_dwordx4 v[146:149], v[86:87], off offset:32
	global_load_dwordx4 v[138:141], v[86:87], off
	s_nop 0
	global_load_dwordx4 v[86:89], v[88:89], off
	s_nop 0
	global_load_dwordx4 v[142:145], v[90:91], off
	s_nop 0
	global_load_dwordx4 v[90:93], v[92:93], off
	s_nop 0
	global_load_dwordx4 v[110:113], v[108:109], off
	global_load_dwordx4 v[126:129], v[106:107], off
	s_cmp_eq_u32 s0, 0
	v_mfma_f32_32x32x16_bf16 v[0:15], v[44:47], v[70:73], v[0:15]
	s_waitcnt vmcnt(10)
	v_mov_b64_e32 v[70:71], v[82:83]
	v_mfma_f32_32x32x16_bf16 v[16:31], v[44:47], v[32:35], v[16:31]
	v_lshl_add_u64 v[32:33], v[52:53], 0, s[2:3]
	v_add_co_u32_e32 v34, vcc, s67, v32
	global_store_dwordx2 v[32:33], v[56:57], off
	global_store_dwordx2 v[32:33], v[60:61], off offset:2048
	v_addc_co_u32_e32 v35, vcc, 0, v33, vcc
	global_store_dwordx2 v[32:33], v[94:95], off offset:512
	global_store_dwordx2 v[32:33], v[96:97], off offset:2560
	global_store_dwordx2 v[34:35], v[58:59], off
	global_store_dwordx2 v[34:35], v[62:63], off offset:2048
	global_store_dwordx2 v[34:35], v[98:99], off offset:512
	global_store_dwordx2 v[34:35], v[100:101], off offset:2560
	v_mfma_f32_32x32x16_bf16 v[0:15], v[36:39], v[48:51], v[0:15]
	v_mov_b64_e32 v[32:33], v[78:79]
	v_mov_b64_e32 v[48:49], v[74:75]
	s_waitcnt vmcnt(12)
	v_mov_b64_e32 v[44:45], v[86:87]
	v_mov_b64_e32 v[34:35], v[80:81]
	v_mov_b64_e32 v[50:51], v[76:77]
	v_mov_b64_e32 v[72:73], v[84:85]
	v_mov_b64_e32 v[46:47], v[88:89]
	v_mfma_f32_32x32x16_bf16 v[16:31], v[36:39], v[40:43], v[16:31]
	v_mov_b64_e32 v[40:41], v[66:67]
	s_waitcnt vmcnt(10)
	v_mov_b64_e32 v[36:37], v[90:91]
	v_mov_b64_e32 v[42:43], v[68:69]
	v_mov_b64_e32 v[38:39], v[92:93]
	s_cbranch_scc0 .LBB0_931
	v_readlane_b32 s0, v246, 24
	v_readlane_b32 s1, v246, 25
	v_cvt_pk_bf16_f32 v0, v0, v1
	v_cvt_pk_bf16_f32 v1, v2, v3
	v_lshl_add_u64 v[32:33], v[52:53], 0, s[0:1]
	global_store_dwordx2 v[32:33], v[0:1], off
	s_mov_b64 s[0:1], -1

; __device__ __forceinline__ void qkt(f32x16& p0, f32x16& p1, const bf16* Ks, const bf16x8* qr, int r32, int hi) {
;   p0 = f32x16{}; p1 = f32x16{};
;   for (int d0 = 0; d0 < 8; ++d0) { int cb = (d0 * 16 + hi * 8) * 2;
;     bf16x8 b0 = *reinterpret_cast<const bf16x8*>((const char*)Ks + KSWZ(r32, cb));
;     bf16x8 b1 = *reinterpret_cast<const bf16x8*>((const char*)Ks + KSWZ(32 + r32, cb));
;     p0 = __builtin_amdgcn_mfma_f32_32x32x16_bf16(b0, qr[d0], p0, 0, 0, 0);
;     p1 = __builtin_amdgcn_mfma_f32_32x32x16_bf16(b1, qr[d0], p1, 0, 0, 0); }
; template <bool WIN> __device__ __forceinline__ void partialSM(f32x16& p0, f32x16& p1, float& m_reg, float& mn, float& alpha, bool rowok, const float* tb, int t0) {
;   if (WIN) {
;     if (rowok) {
; #pragma unroll
;       for (int r = 0; r < 16; ++r) { const int cr = (r & 3) + 8 * (r >> 2);
;         const float b0 = tb[cr], b1 = tb[cr + 32];
;         p0[r] = ((unsigned)(cr + t0) < 16u) ? fmaf(p0[r], C2, b0) : NEGB;
;         p1[r] = ((unsigned)(cr + 32 + t0) < 16u) ? fmaf(p1[r], C2, b1) : NEGB; }
;     } else {
; #pragma unroll
;       for (int r = 0; r < 16; ++r) { p0[r] = NEGB; p1[r] = NEGB; }
;     }
;   } else {
; #pragma unroll
;     for (int r = 0; r < 16; ++r) { p0[r] *= C2; p1[r] *= C2; }
;   }
;   float pmax = p0[0];
; #pragma unroll
;   for (int r = 1; r < 16; ++r) pmax = fmaxf(pmax, p0[r]);
; #pragma unroll
;   for (int r = 0; r < 16; ++r) pmax = fmaxf(pmax, p1[r]);
;   { auto rr = __builtin_amdgcn_permlane32_swap(__float_as_uint(pmax), __float_as_uint(pmax), false, false);
;     pmax = fmaxf(__uint_as_float(rr[0]), __uint_as_float(rr[1])); }
.LBB0_949:
	s_add_i32 s4, s9, 0
	v_add3_u32 v228, s4, v217, v216
	ds_read_b128 v[66:69], v228 offset:32768
	ds_read_b128 v[82:85], v228 offset:40960
	v_add3_u32 v228, s4, v218, v216
	ds_read_b128 v[182:185], v228 offset:32768
	ds_read_b128 v[186:189], v228 offset:40960
	v_add3_u32 v228, s4, v219, v216
	ds_read_b128 v[190:193], v228 offset:32768
	ds_read_b128 v[194:197], v228 offset:40960
	s_waitcnt lgkmcnt(5)
	v_mfma_f32_32x32x16_bf16 v[66:81], v[66:69], v[98:101], 0
	s_waitcnt lgkmcnt(4)
	v_mfma_f32_32x32x16_bf16 v[82:97], v[82:85], v[98:101], 0
	s_waitcnt lgkmcnt(3)
	v_mfma_f32_32x32x16_bf16 v[66:81], v[182:185], v[102:105], v[66:81]
	s_waitcnt lgkmcnt(2)
	v_mfma_f32_32x32x16_bf16 v[82:97], v[186:189], v[102:105], v[82:97]
	v_add3_u32 v228, s4, v220, v216
	ds_read_b128 v[182:185], v228 offset:32768
	ds_read_b128 v[186:189], v228 offset:40960
	s_waitcnt lgkmcnt(3)
	v_mfma_f32_32x32x16_bf16 v[66:81], v[190:193], v[106:109], v[66:81]
	s_waitcnt lgkmcnt(2)
	v_mfma_f32_32x32x16_bf16 v[82:97], v[194:197], v[106:109], v[82:97]
	v_add3_u32 v228, s4, v221, v216
	ds_read_b128 v[190:193], v228 offset:32768
	ds_read_b128 v[194:197], v228 offset:40960
	s_waitcnt lgkmcnt(3)
	v_mfma_f32_32x32x16_bf16 v[66:81], v[182:185], v[110:113], v[66:81]
	s_waitcnt lgkmcnt(2)
	v_mfma_f32_32x32x16_bf16 v[82:97], v[186:189], v[110:113], v[82:97]
	v_add3_u32 v228, s4, v222, v216
	ds_read_b128 v[182:185], v228 offset:32768
	ds_read_b128 v[186:189], v228 offset:40960
	s_waitcnt lgkmcnt(3)
	v_mfma_f32_32x32x16_bf16 v[66:81], v[190:193], v[114:117], v[66:81]
	s_waitcnt lgkmcnt(2)
	v_mfma_f32_32x32x16_bf16 v[82:97], v[194:197], v[114:117], v[82:97]
	v_add3_u32 v228, s4, v223, v216
	ds_read_b128 v[190:193], v228 offset:32768
	ds_read_b128 v[194:197], v228 offset:40960
	s_waitcnt lgkmcnt(3)
	v_mfma_f32_32x32x16_bf16 v[66:81], v[182:185], v[118:121], v[66:81]
	s_waitcnt lgkmcnt(2)
	v_mfma_f32_32x32x16_bf16 v[82:97], v[186:189], v[118:121], v[82:97]
	v_add3_u32 v228, s4, v224, v216
	ds_read_b128 v[182:185], v228 offset:32768
	ds_read_b128 v[186:189], v228 offset:40960
	s_waitcnt lgkmcnt(3)
	v_mfma_f32_32x32x16_bf16 v[66:81], v[190:193], v[122:125], v[66:81]
	s_waitcnt lgkmcnt(2)
	v_mfma_f32_32x32x16_bf16 v[82:97], v[194:197], v[122:125], v[82:97]
	s_waitcnt lgkmcnt(1)
	v_mfma_f32_32x32x16_bf16 v[66:81], v[182:185], v[126:129], v[66:81]
	s_waitcnt lgkmcnt(0)
	v_mfma_f32_32x32x16_bf16 v[82:97], v[186:189], v[126:129], v[82:97]
	s_mov_b32 s4, 0x4138aa3b
	s_nop 8
	v_mul_f32_e32 v64, 0x3e0293ee, v66
	v_mul_f32_e32 v179, 0x3e0293ee, v67
	v_mul_f32_e32 v181, 0x3e0293ee, v68
	v_mul_f32_e32 v183, 0x3e0293ee, v69
	v_max_f32_e32 v64, v64, v179
	v_mul_f32_e32 v185, 0x3e0293ee, v70
	v_mul_f32_e32 v187, 0x3e0293ee, v71
	v_max3_f32 v64, v64, v181, v183
	v_mul_f32_e32 v189, 0x3e0293ee, v72
	v_mul_f32_e32 v191, 0x3e0293ee, v73
	v_max3_f32 v64, v64, v185, v187
	v_mul_f32_e32 v193, 0x3e0293ee, v74
	v_mul_f32_e32 v195, 0x3e0293ee, v75
	v_max3_f32 v64, v64, v189, v191
	v_mul_f32_e32 v197, 0x3e0293ee, v76
	v_mul_f32_e32 v229, 0x3e0293ee, v77
	v_max3_f32 v64, v64, v193, v195
	v_mul_f32_e32 v231, 0x3e0293ee, v78
	v_mul_f32_e32 v233, 0x3e0293ee, v79
	v_max3_f32 v64, v64, v197, v229
	v_mul_f32_e32 v235, 0x3e0293ee, v80
	v_mul_f32_e32 v237, 0x3e0293ee, v81
	v_max3_f32 v64, v64, v231, v233
	v_mul_f32_e32 v178, 0x3e0293ee, v82
	v_mul_f32_e32 v180, 0x3e0293ee, v83
	v_max3_f32 v64, v64, v235, v237
	v_mul_f32_e32 v182, 0x3e0293ee, v84
	v_mul_f32_e32 v184, 0x3e0293ee, v85
	v_max3_f32 v64, v64, v178, v180
	v_mul_f32_e32 v186, 0x3e0293ee, v86
	v_mul_f32_e32 v188, 0x3e0293ee, v87
	v_max3_f32 v64, v64, v182, v184
	v_mul_f32_e32 v190, 0x3e0293ee, v88
	v_mul_f32_e32 v192, 0x3e0293ee, v89
	v_max3_f32 v64, v64, v186, v188
	v_mul_f32_e32 v194, 0x3e0293ee, v90
	v_mul_f32_e32 v196, 0x3e0293ee, v91
	v_max3_f32 v64, v64, v190, v192
	v_mul_f32_e32 v228, 0x3e0293ee, v92
	v_mul_f32_e32 v230, 0x3e0293ee, v93
	v_max3_f32 v64, v64, v194, v196
	v_mul_f32_e32 v232, 0x3e0293ee, v94
	v_mul_f32_e32 v234, 0x3e0293ee, v95
	v_max3_f32 v64, v64, v228, v230
	v_mul_f32_e32 v236, 0x3e0293ee, v96
	v_mul_f32_e32 v238, 0x3e0293ee, v97
	v_max3_f32 v64, v64, v232, v234
	v_max3_f32 v64, v64, v236, v238
	v_mov_b32_e32 v178, v64
	s_nop 1
	v_permlane32_swap_b32_e32 v64, v178
	v_max_f32_e32 v178, v178, v178
	v_max_f32_e32 v64, v64, v64
	v_max_f32_e32 v64, v64, v178
	v_sub_f32_e32 v178, v64, v160
	v_cmp_ge_f32_e32 vcc, s4, v178
	v_max_f32_e32 v179, v160, v160
	s_cmp_eq_u64 vcc, exec
	v_max_f32_e32 v179, v179, v64
	s_cselect_b64 vcc, -1, 0
	v_sub_f32_e32 v64, v160, v179
	v_cndmask_b32_e32 v160, v179, v160, vcc
	s_mov_b32 s4, 0x3e0293ee
	v_fma_f32 v66, v66, s4, -v160
	v_fma_f32 v67, v67, s4, -v160
	v_exp_f32_e32 v66, v66
	v_fma_f32 v68, v68, s4, -v160
	v_exp_f32_e32 v67, v67
	v_fma_f32 v69, v69, s4, -v160
	v_exp_f32_e32 v68, v68
	v_fma_f32 v82, v82, s4, -v160
	v_fma_f32 v70, v70, s4, -v160
	v_exp_f32_e32 v69, v69
	v_fma_f32 v71, v71, s4, -v160
	v_exp_f32_e32 v70, v70
	v_exp_f32_e32 v178, v82
	v_add_f32_e32 v82, 0, v66
	v_fma_f32 v72, v72, s4, -v160
; __device__ __forceinline__ void finishSM(f32x16& p0, f32x16& p1, float alpha, float& l_reg, bf16x8& pa0, bf16x8& pa1, bf16x8& pa2, bf16x8& pa3) {
;   for (int r = 0; r < 16; ++r) p1[r] = __builtin_amdgcn_exp2f(p1[r]);
;   float ps = 0; for (int r = 0; r < 16; ++r) ps += p0[r]; for (int r = 0; r < 16; ++r) ps += p1[r];
;   { auto rr = __builtin_amdgcn_permlane32_swap(__float_as_uint(ps), __float_as_uint(ps), false, false);
;     ps = __uint_as_float(rr[0]) + __uint_as_float(rr[1]); }
;   l_reg = l_reg * alpha + ps;
;     ...
;   PK4(p0, 0, pa0); PK4(p0, 8, pa1); PK4(p1, 0, pa2); PK4(p1, 8, pa3);
;     ...
; }
; template <bool WIN> __device__ __forceinline__ void partialSM(f32x16& p0, f32x16& p1, float& m_reg, float& mn, float& alpha, bool rowok, const float* tb, int t0) {
;     ...
;   else { mn = fmaxf(m_reg, pmax); alpha = __builtin_amdgcn_exp2f(m_reg - mn); m_reg = mn; }
; #pragma unroll
;   for (int r = 0; r < 16; ++r) { p0[r] -= mn; p1[r] -= mn; }
; #pragma unroll
;   for (int r = 0; r < 16; ++r) p0[r] = __builtin_amdgcn_exp2f(p0[r]);
	v_exp_f32_e32 v71, v71
	v_add_f32_e32 v82, v67, v82
	v_fma_f32 v73, v73, s4, -v160
	v_exp_f32_e32 v72, v72
	v_add_f32_e32 v82, v68, v82
	v_fma_f32 v74, v74, s4, -v160
	v_exp_f32_e32 v73, v73
	v_add_f32_e32 v82, v69, v82
	v_fma_f32 v75, v75, s4, -v160
	v_exp_f32_e32 v74, v74
	v_add_f32_e32 v82, v70, v82
	v_fma_f32 v76, v76, s4, -v160
	v_exp_f32_e32 v75, v75
	v_add_f32_e32 v82, v71, v82
	v_fma_f32 v77, v77, s4, -v160
	v_exp_f32_e32 v76, v76
	v_add_f32_e32 v82, v72, v82
	v_fma_f32 v78, v78, s4, -v160
	v_exp_f32_e32 v77, v77
	v_add_f32_e32 v82, v73, v82
	v_fma_f32 v79, v79, s4, -v160
	v_exp_f32_e32 v78, v78
	v_add_f32_e32 v82, v74, v82
	v_fma_f32 v80, v80, s4, -v160
	v_exp_f32_e32 v79, v79
	v_add_f32_e32 v82, v75, v82
	v_fma_f32 v81, v81, s4, -v160
	v_exp_f32_e32 v80, v80
	v_add_f32_e32 v82, v76, v82
	v_exp_f32_e32 v81, v81
	v_add_f32_e32 v82, v77, v82
	v_fma_f32 v83, v83, s4, -v160
	v_add_f32_e32 v82, v78, v82
	v_fma_f32 v84, v84, s4, -v160
	v_exp_f32_e32 v179, v83
	v_add_f32_e32 v82, v79, v82
	v_fma_f32 v85, v85, s4, -v160
	v_exp_f32_e32 v84, v84
	v_add_f32_e32 v82, v80, v82
	v_fma_f32 v86, v86, s4, -v160
	v_exp_f32_e32 v85, v85
	v_add_f32_e32 v82, v81, v82
	v_fma_f32 v87, v87, s4, -v160
	v_exp_f32_e32 v86, v86
	v_add_f32_e32 v82, v178, v82
	v_fma_f32 v88, v88, s4, -v160
	v_exp_f32_e32 v87, v87
	v_add_f32_e32 v82, v179, v82
	v_fma_f32 v89, v89, s4, -v160
	v_exp_f32_e32 v88, v88
	v_add_f32_e32 v82, v84, v82
	v_fma_f32 v90, v90, s4, -v160
	v_exp_f32_e32 v89, v89
	v_add_f32_e32 v82, v85, v82
	v_fma_f32 v91, v91, s4, -v160
	v_exp_f32_e32 v90, v90
	v_add_f32_e32 v82, v86, v82
	v_fma_f32 v92, v92, s4, -v160
	v_exp_f32_e32 v91, v91
	v_add_f32_e32 v82, v87, v82
	v_fma_f32 v93, v93, s4, -v160
	v_exp_f32_e32 v92, v92
	v_add_f32_e32 v82, v88, v82
	v_fma_f32 v94, v94, s4, -v160
	v_exp_f32_e32 v93, v93
	v_add_f32_e32 v82, v89, v82
	v_fma_f32 v95, v95, s4, -v160
	v_exp_f32_e32 v94, v94
	v_add_f32_e32 v82, v90, v82
	v_fma_f32 v96, v96, s4, -v160
	v_exp_f32_e32 v95, v95
	v_add_f32_e32 v82, v91, v82
	v_fma_f32 v97, v97, s4, -v160
	v_exp_f32_e32 v96, v96
	v_add_f32_e32 v82, v92, v82
	v_exp_f32_e32 v97, v97
	v_add_f32_e32 v82, v93, v82
	v_add_f32_e32 v82, v94, v82
	v_exp_f32_e32 v64, v64
	v_add_f32_e32 v82, v95, v82
	v_add_f32_e32 v82, v96, v82
	v_add_f32_e32 v82, v97, v82
	v_mov_b32_e32 v83, v82
	v_cvt_pk_bf16_f32 v66, v66, v67
	v_cvt_pk_bf16_f32 v67, v68, v69
	v_cvt_pk_bf16_f32 v68, v70, v71
	v_cvt_pk_bf16_f32 v69, v72, v73
	v_cvt_pk_bf16_f32 v70, v74, v75
	v_cvt_pk_bf16_f32 v71, v76, v77
	v_cvt_pk_bf16_f32 v72, v78, v79
	v_cvt_pk_bf16_f32 v73, v80, v81
	v_cvt_pk_bf16_f32 v78, v178, v179
	v_cvt_pk_bf16_f32 v79, v84, v85
	v_cvt_pk_bf16_f32 v80, v86, v87
	v_cvt_pk_bf16_f32 v81, v88, v89
	v_cvt_pk_bf16_f32 v74, v90, v91
	v_cvt_pk_bf16_f32 v75, v92, v93
	v_cvt_pk_bf16_f32 v76, v94, v95
	v_cvt_pk_bf16_f32 v77, v96, v97
	v_cndmask_b32_e64 v64, v64, 1.0, vcc
	s_nop 0
	v_permlane32_swap_b32_e32 v82, v83
	v_permlane32_swap_b32_e32 v66, v68
	v_permlane32_swap_b32_e32 v67, v69
	v_permlane32_swap_b32_e32 v70, v72
	v_permlane32_swap_b32_e32 v71, v73
	v_permlane32_swap_b32_e32 v78, v80
	v_permlane32_swap_b32_e32 v79, v81
	v_permlane32_swap_b32_e32 v74, v76
	v_permlane32_swap_b32_e32 v75, v77
	v_cmp_gt_f32_e32 vcc, 1.0, v64
	s_cbranch_vccz .LBB0_953
	s_and_saveexec_b64 s[4:5], s[40:41]
	ds_write_b32 v159, v64 offset:128
	s_or_b64 exec, exec, s[4:5]
	s_waitcnt lgkmcnt(0)
	ds_read_b128 v[84:87], v158 offset:224
	ds_read_b128 v[88:91], v158 offset:192
	ds_read_b128 v[92:95], v158 offset:160
	ds_read_b128 v[178:181], v158 offset:128
	s_waitcnt lgkmcnt(3)
	v_pk_mul_f32 v[62:63], v[62:63], v[86:87]
	s_waitcnt lgkmcnt(2)
	v_pk_mul_f32 v[58:59], v[58:59], v[90:91]
	s_waitcnt lgkmcnt(1)
	v_pk_mul_f32 v[54:55], v[54:55], v[94:95]
	s_waitcnt lgkmcnt(0)
	v_pk_mul_f32 v[50:51], v[50:51], v[180:181]
	v_pk_mul_f32 v[60:61], v[60:61], v[84:85]
	v_pk_mul_f32 v[56:57], v[56:57], v[88:89]
	v_pk_mul_f32 v[52:53], v[52:53], v[92:93]
	v_pk_mul_f32 v[48:49], v[48:49], v[178:179]
	v_pk_mul_f32 v[46:47], v[46:47], v[86:87]
	v_pk_mul_f32 v[42:43], v[42:43], v[90:91]
	v_pk_mul_f32 v[38:39], v[38:39], v[94:95]
	v_pk_mul_f32 v[34:35], v[34:35], v[180:181]
	v_pk_mul_f32 v[44:45], v[44:45], v[84:85]
	v_pk_mul_f32 v[40:41], v[40:41], v[88:89]
	v_pk_mul_f32 v[36:37], v[36:37], v[92:93]
	v_pk_mul_f32 v[32:33], v[32:33], v[178:179]
	v_pk_mul_f32 v[30:31], v[30:31], v[86:87]
	v_pk_mul_f32 v[26:27], v[26:27], v[90:91]
	v_pk_mul_f32 v[22:23], v[22:23], v[94:95]
	v_pk_mul_f32 v[18:19], v[18:19], v[180:181]
	v_pk_mul_f32 v[28:29], v[28:29], v[84:85]
	v_pk_mul_f32 v[24:25], v[24:25], v[88:89]
	v_pk_mul_f32 v[20:21], v[20:21], v[92:93]
	v_pk_mul_f32 v[16:17], v[16:17], v[178:179]
	v_pk_mul_f32 v[14:15], v[14:15], v[86:87]
	v_pk_mul_f32 v[10:11], v[10:11], v[90:91]
	v_pk_mul_f32 v[6:7], v[6:7], v[94:95]
	v_pk_mul_f32 v[2:3], v[2:3], v[180:181]
	v_pk_mul_f32 v[12:13], v[12:13], v[84:85]
	v_pk_mul_f32 v[8:9], v[8:9], v[88:89]
	v_pk_mul_f32 v[4:5], v[4:5], v[92:93]
	v_pk_mul_f32 v[0:1], v[0:1], v[178:179]
